# up-projection: left-over pair tiles cut into 16 single-tile pieces (16 workgroups per XCD), packed-f32 instructions for the non-transcendental epilogue math
# speedup vs baseline: 1.0034x; 1.0034x over previous
.Lg2_a_kdone3:
	s_nop 7
	s_nop 1
	v_mov_b32_e32 v166, 0xbfb8aa3b
	v_mov_b32_e32 v167, 0xbfb8aa3b
	v_mov_b32_e32 v178, 1.0
	v_mov_b32_e32 v179, 1.0
	v_mov_b32_e32 v176, v138
	v_pk_mul_f32 v[162:163], v[2:3], v[166:167]
	v_pk_mul_f32 v[164:165], v[4:5], v[166:167]
	v_exp_f32_e32 v162, v162
	v_exp_f32_e32 v163, v163
	v_exp_f32_e32 v164, v164
	v_exp_f32_e32 v165, v165
	v_pk_add_f32 v[162:163], v[162:163], v[178:179]
	v_pk_add_f32 v[164:165], v[164:165], v[178:179]
	v_rcp_f32_e32 v162, v162
	v_rcp_f32_e32 v163, v163
	v_rcp_f32_e32 v164, v164
	v_rcp_f32_e32 v165, v165
	v_pk_mul_f32 v[162:163], v[2:3], v[162:163]
	v_pk_mul_f32 v[164:165], v[4:5], v[164:165]
	v_pk_mul_f32 v[162:163], v[10:11], v[162:163]
	v_pk_mul_f32 v[164:165], v[12:13], v[164:165]
	v_cvt_pk_bf16_f32 v168, v162, v163
	v_cvt_pk_bf16_f32 v169, v164, v165
	v_pk_mul_f32 v[162:163], v[6:7], v[166:167]
	v_pk_mul_f32 v[164:165], v[8:9], v[166:167]
	v_exp_f32_e32 v162, v162
	v_exp_f32_e32 v163, v163
	v_exp_f32_e32 v164, v164
	v_exp_f32_e32 v165, v165
	v_pk_add_f32 v[162:163], v[162:163], v[178:179]
	v_pk_add_f32 v[164:165], v[164:165], v[178:179]
	v_rcp_f32_e32 v162, v162
	v_rcp_f32_e32 v163, v163
	v_rcp_f32_e32 v164, v164
	v_rcp_f32_e32 v165, v165
	v_pk_mul_f32 v[162:163], v[6:7], v[162:163]
	v_pk_mul_f32 v[164:165], v[8:9], v[164:165]
	v_pk_mul_f32 v[162:163], v[14:15], v[162:163]
	v_pk_mul_f32 v[164:165], v[16:17], v[164:165]
	v_cvt_pk_bf16_f32 v170, v162, v163
	v_cvt_pk_bf16_f32 v171, v164, v165
	s_nop 1
	v_permlane16_swap_b32_e32 v168, v170
	v_permlane16_swap_b32_e32 v169, v171
	global_store_dwordx4 v176, v[168:171], s[4:5] offset:0 sc1
	v_pk_mul_f32 v[162:163], v[66:67], v[166:167]
	v_pk_mul_f32 v[164:165], v[68:69], v[166:167]
	v_exp_f32_e32 v162, v162
	v_exp_f32_e32 v163, v163
	v_exp_f32_e32 v164, v164
	v_exp_f32_e32 v165, v165
	v_pk_add_f32 v[162:163], v[162:163], v[178:179]
	v_pk_add_f32 v[164:165], v[164:165], v[178:179]
	v_rcp_f32_e32 v162, v162
	v_rcp_f32_e32 v163, v163
	v_rcp_f32_e32 v164, v164
	v_rcp_f32_e32 v165, v165
	v_pk_mul_f32 v[162:163], v[66:67], v[162:163]
	v_pk_mul_f32 v[164:165], v[68:69], v[164:165]
	v_pk_mul_f32 v[162:163], v[74:75], v[162:163]
	v_pk_mul_f32 v[164:165], v[76:77], v[164:165]
	v_cvt_pk_bf16_f32 v172, v162, v163
	v_cvt_pk_bf16_f32 v173, v164, v165
	v_pk_mul_f32 v[162:163], v[70:71], v[166:167]
	v_pk_mul_f32 v[164:165], v[72:73], v[166:167]
	v_exp_f32_e32 v162, v162
	v_exp_f32_e32 v163, v163
	v_exp_f32_e32 v164, v164
	v_exp_f32_e32 v165, v165
	v_pk_add_f32 v[162:163], v[162:163], v[178:179]
	v_pk_add_f32 v[164:165], v[164:165], v[178:179]
	v_rcp_f32_e32 v162, v162
	v_rcp_f32_e32 v163, v163
	v_rcp_f32_e32 v164, v164
	v_rcp_f32_e32 v165, v165
	v_pk_mul_f32 v[162:163], v[70:71], v[162:163]
	v_pk_mul_f32 v[164:165], v[72:73], v[164:165]
	v_pk_mul_f32 v[162:163], v[78:79], v[162:163]
	v_pk_mul_f32 v[164:165], v[80:81], v[164:165]
	v_cvt_pk_bf16_f32 v174, v162, v163
	v_cvt_pk_bf16_f32 v175, v164, v165
	s_nop 1
	v_permlane16_swap_b32_e32 v172, v174
	v_permlane16_swap_b32_e32 v173, v175
	global_store_dwordx4 v176, v[172:175], s[4:5] offset:2048 sc1
	v_add_u32_e32 v176, 0x16000, v176
	v_pk_mul_f32 v[162:163], v[18:19], v[166:167]
	v_pk_mul_f32 v[164:165], v[20:21], v[166:167]
	v_exp_f32_e32 v162, v162
	v_exp_f32_e32 v163, v163
	v_exp_f32_e32 v164, v164
	v_exp_f32_e32 v165, v165
	v_pk_add_f32 v[162:163], v[162:163], v[178:179]
	v_pk_add_f32 v[164:165], v[164:165], v[178:179]
	v_rcp_f32_e32 v162, v162
	v_rcp_f32_e32 v163, v163
	v_rcp_f32_e32 v164, v164
	v_rcp_f32_e32 v165, v165
	v_pk_mul_f32 v[162:163], v[18:19], v[162:163]
	v_pk_mul_f32 v[164:165], v[20:21], v[164:165]
	v_pk_mul_f32 v[162:163], v[26:27], v[162:163]
	v_pk_mul_f32 v[164:165], v[28:29], v[164:165]
	v_cvt_pk_bf16_f32 v168, v162, v163
	v_cvt_pk_bf16_f32 v169, v164, v165
	v_pk_mul_f32 v[162:163], v[22:23], v[166:167]
	v_pk_mul_f32 v[164:165], v[24:25], v[166:167]
	v_exp_f32_e32 v162, v162
	v_exp_f32_e32 v163, v163
	v_exp_f32_e32 v164, v164
	v_exp_f32_e32 v165, v165
	v_pk_add_f32 v[162:163], v[162:163], v[178:179]
	v_pk_add_f32 v[164:165], v[164:165], v[178:179]
	v_rcp_f32_e32 v162, v162
	v_rcp_f32_e32 v163, v163
	v_rcp_f32_e32 v164, v164
	v_rcp_f32_e32 v165, v165
	v_pk_mul_f32 v[162:163], v[22:23], v[162:163]
	v_pk_mul_f32 v[164:165], v[24:25], v[164:165]
	v_pk_mul_f32 v[162:163], v[30:31], v[162:163]
	v_pk_mul_f32 v[164:165], v[32:33], v[164:165]
	v_cvt_pk_bf16_f32 v170, v162, v163
	v_cvt_pk_bf16_f32 v171, v164, v165
	s_nop 1
	v_permlane16_swap_b32_e32 v168, v170
	v_permlane16_swap_b32_e32 v169, v171
	global_store_dwordx4 v176, v[168:171], s[4:5] offset:0 sc1
	v_pk_mul_f32 v[162:163], v[82:83], v[166:167]
	v_pk_mul_f32 v[164:165], v[84:85], v[166:167]
	v_exp_f32_e32 v162, v162
	v_exp_f32_e32 v163, v163
	v_exp_f32_e32 v164, v164
	v_exp_f32_e32 v165, v165
	v_pk_add_f32 v[162:163], v[162:163], v[178:179]
	v_pk_add_f32 v[164:165], v[164:165], v[178:179]
	v_rcp_f32_e32 v162, v162
	v_rcp_f32_e32 v163, v163
	v_rcp_f32_e32 v164, v164
	v_rcp_f32_e32 v165, v165
	v_pk_mul_f32 v[162:163], v[82:83], v[162:163]
	v_pk_mul_f32 v[164:165], v[84:85], v[164:165]
	v_pk_mul_f32 v[162:163], v[90:91], v[162:163]
	v_pk_mul_f32 v[164:165], v[92:93], v[164:165]
	v_cvt_pk_bf16_f32 v172, v162, v163
	v_cvt_pk_bf16_f32 v173, v164, v165
	v_pk_mul_f32 v[162:163], v[86:87], v[166:167]
	v_pk_mul_f32 v[164:165], v[88:89], v[166:167]
	v_exp_f32_e32 v162, v162
	v_exp_f32_e32 v163, v163
	v_exp_f32_e32 v164, v164
	v_exp_f32_e32 v165, v165
	v_pk_add_f32 v[162:163], v[162:163], v[178:179]
	v_pk_add_f32 v[164:165], v[164:165], v[178:179]
	v_rcp_f32_e32 v162, v162
	v_rcp_f32_e32 v163, v163
	v_rcp_f32_e32 v164, v164
	v_rcp_f32_e32 v165, v165
	v_pk_mul_f32 v[162:163], v[86:87], v[162:163]
	v_pk_mul_f32 v[164:165], v[88:89], v[164:165]
	v_pk_mul_f32 v[162:163], v[94:95], v[162:163]
	v_pk_mul_f32 v[164:165], v[96:97], v[164:165]
	v_cvt_pk_bf16_f32 v174, v162, v163
	v_cvt_pk_bf16_f32 v175, v164, v165
	s_nop 1
	v_permlane16_swap_b32_e32 v172, v174
	v_permlane16_swap_b32_e32 v173, v175
	global_store_dwordx4 v176, v[172:175], s[4:5] offset:2048 sc1
	v_add_u32_e32 v176, 0x16000, v176
	v_pk_mul_f32 v[162:163], v[34:35], v[166:167]
	v_pk_mul_f32 v[164:165], v[36:37], v[166:167]
	v_exp_f32_e32 v162, v162
	v_exp_f32_e32 v163, v163
	v_exp_f32_e32 v164, v164
	v_exp_f32_e32 v165, v165
	v_pk_add_f32 v[162:163], v[162:163], v[178:179]
	v_pk_add_f32 v[164:165], v[164:165], v[178:179]
	v_rcp_f32_e32 v162, v162
	v_rcp_f32_e32 v163, v163
	v_rcp_f32_e32 v164, v164
	v_rcp_f32_e32 v165, v165
	v_pk_mul_f32 v[162:163], v[34:35], v[162:163]
	v_pk_mul_f32 v[164:165], v[36:37], v[164:165]
	v_pk_mul_f32 v[162:163], v[42:43], v[162:163]
	v_pk_mul_f32 v[164:165], v[44:45], v[164:165]
	v_cvt_pk_bf16_f32 v168, v162, v163
	v_cvt_pk_bf16_f32 v169, v164, v165
	v_pk_mul_f32 v[162:163], v[38:39], v[166:167]
	v_pk_mul_f32 v[164:165], v[40:41], v[166:167]
	v_exp_f32_e32 v162, v162
	v_exp_f32_e32 v163, v163
	v_exp_f32_e32 v164, v164
	v_exp_f32_e32 v165, v165
	v_pk_add_f32 v[162:163], v[162:163], v[178:179]
	v_pk_add_f32 v[164:165], v[164:165], v[178:179]
	v_rcp_f32_e32 v162, v162
	v_rcp_f32_e32 v163, v163
	v_rcp_f32_e32 v164, v164
	v_rcp_f32_e32 v165, v165
	v_pk_mul_f32 v[162:163], v[38:39], v[162:163]
	v_pk_mul_f32 v[164:165], v[40:41], v[164:165]
	v_pk_mul_f32 v[162:163], v[46:47], v[162:163]
	v_pk_mul_f32 v[164:165], v[48:49], v[164:165]
	v_cvt_pk_bf16_f32 v170, v162, v163
	v_cvt_pk_bf16_f32 v171, v164, v165
	s_nop 1
	v_permlane16_swap_b32_e32 v168, v170
	v_permlane16_swap_b32_e32 v169, v171
	global_store_dwordx4 v176, v[168:171], s[4:5] offset:0 sc1
	v_pk_mul_f32 v[162:163], v[98:99], v[166:167]
	v_pk_mul_f32 v[164:165], v[100:101], v[166:167]
	v_exp_f32_e32 v162, v162
	v_exp_f32_e32 v163, v163
	v_exp_f32_e32 v164, v164
	v_exp_f32_e32 v165, v165
	v_pk_add_f32 v[162:163], v[162:163], v[178:179]
	v_pk_add_f32 v[164:165], v[164:165], v[178:179]
	v_rcp_f32_e32 v162, v162
	v_rcp_f32_e32 v163, v163
	v_rcp_f32_e32 v164, v164
	v_rcp_f32_e32 v165, v165
	v_pk_mul_f32 v[162:163], v[98:99], v[162:163]
	v_pk_mul_f32 v[164:165], v[100:101], v[164:165]
	v_pk_mul_f32 v[162:163], v[106:107], v[162:163]
	v_pk_mul_f32 v[164:165], v[108:109], v[164:165]
	v_cvt_pk_bf16_f32 v172, v162, v163
	v_cvt_pk_bf16_f32 v173, v164, v165
	v_pk_mul_f32 v[162:163], v[102:103], v[166:167]
	v_pk_mul_f32 v[164:165], v[104:105], v[166:167]
	v_exp_f32_e32 v162, v162
	v_exp_f32_e32 v163, v163
	v_exp_f32_e32 v164, v164
	v_exp_f32_e32 v165, v165
	v_pk_add_f32 v[162:163], v[162:163], v[178:179]
	v_pk_add_f32 v[164:165], v[164:165], v[178:179]
	v_rcp_f32_e32 v162, v162
	v_rcp_f32_e32 v163, v163
	v_rcp_f32_e32 v164, v164
	v_rcp_f32_e32 v165, v165
	v_pk_mul_f32 v[162:163], v[102:103], v[162:163]
	v_pk_mul_f32 v[164:165], v[104:105], v[164:165]
	v_pk_mul_f32 v[162:163], v[110:111], v[162:163]
	v_pk_mul_f32 v[164:165], v[112:113], v[164:165]
	v_cvt_pk_bf16_f32 v174, v162, v163
	v_cvt_pk_bf16_f32 v175, v164, v165
	s_nop 1
	v_permlane16_swap_b32_e32 v172, v174
	v_permlane16_swap_b32_e32 v173, v175
	global_store_dwordx4 v176, v[172:175], s[4:5] offset:2048 sc1
	v_add_u32_e32 v176, 0x16000, v176
	v_pk_mul_f32 v[162:163], v[50:51], v[166:167]
	v_pk_mul_f32 v[164:165], v[52:53], v[166:167]
	v_exp_f32_e32 v162, v162
	v_exp_f32_e32 v163, v163
	v_exp_f32_e32 v164, v164
	v_exp_f32_e32 v165, v165
	v_pk_add_f32 v[162:163], v[162:163], v[178:179]
	v_pk_add_f32 v[164:165], v[164:165], v[178:179]
	v_rcp_f32_e32 v162, v162
	v_rcp_f32_e32 v163, v163
	v_rcp_f32_e32 v164, v164
	v_rcp_f32_e32 v165, v165
	v_pk_mul_f32 v[162:163], v[50:51], v[162:163]
	v_pk_mul_f32 v[164:165], v[52:53], v[164:165]
	v_pk_mul_f32 v[162:163], v[58:59], v[162:163]
	v_pk_mul_f32 v[164:165], v[60:61], v[164:165]
	v_cvt_pk_bf16_f32 v168, v162, v163
	v_cvt_pk_bf16_f32 v169, v164, v165
	v_pk_mul_f32 v[162:163], v[54:55], v[166:167]
	v_pk_mul_f32 v[164:165], v[56:57], v[166:167]
	v_exp_f32_e32 v162, v162
	v_exp_f32_e32 v163, v163
	v_exp_f32_e32 v164, v164
	v_exp_f32_e32 v165, v165
	v_pk_add_f32 v[162:163], v[162:163], v[178:179]
	v_pk_add_f32 v[164:165], v[164:165], v[178:179]
	v_rcp_f32_e32 v162, v162
	v_rcp_f32_e32 v163, v163
	v_rcp_f32_e32 v164, v164
	v_rcp_f32_e32 v165, v165
	v_pk_mul_f32 v[162:163], v[54:55], v[162:163]
	v_pk_mul_f32 v[164:165], v[56:57], v[164:165]
	v_pk_mul_f32 v[162:163], v[62:63], v[162:163]
	v_pk_mul_f32 v[164:165], v[64:65], v[164:165]
	v_cvt_pk_bf16_f32 v170, v162, v163
	v_cvt_pk_bf16_f32 v171, v164, v165
	s_nop 1
	v_permlane16_swap_b32_e32 v168, v170
	v_permlane16_swap_b32_e32 v169, v171
	global_store_dwordx4 v176, v[168:171], s[4:5] offset:0 sc1
	v_pk_mul_f32 v[162:163], v[114:115], v[166:167]
	v_pk_mul_f32 v[164:165], v[116:117], v[166:167]
	v_exp_f32_e32 v162, v162
	v_exp_f32_e32 v163, v163
	v_exp_f32_e32 v164, v164
	v_exp_f32_e32 v165, v165
	v_pk_add_f32 v[162:163], v[162:163], v[178:179]
	v_pk_add_f32 v[164:165], v[164:165], v[178:179]
	v_rcp_f32_e32 v162, v162
	v_rcp_f32_e32 v163, v163
	v_rcp_f32_e32 v164, v164
	v_rcp_f32_e32 v165, v165
	v_pk_mul_f32 v[162:163], v[114:115], v[162:163]
	v_pk_mul_f32 v[164:165], v[116:117], v[164:165]
	v_pk_mul_f32 v[162:163], v[122:123], v[162:163]
	v_pk_mul_f32 v[164:165], v[124:125], v[164:165]
	v_cvt_pk_bf16_f32 v172, v162, v163
	v_cvt_pk_bf16_f32 v173, v164, v165
	v_pk_mul_f32 v[162:163], v[118:119], v[166:167]
	v_pk_mul_f32 v[164:165], v[120:121], v[166:167]
	v_exp_f32_e32 v162, v162
	v_exp_f32_e32 v163, v163
	v_exp_f32_e32 v164, v164
	v_exp_f32_e32 v165, v165
	v_pk_add_f32 v[162:163], v[162:163], v[178:179]
	v_pk_add_f32 v[164:165], v[164:165], v[178:179]
	v_rcp_f32_e32 v162, v162
	v_rcp_f32_e32 v163, v163
	v_rcp_f32_e32 v164, v164
	v_rcp_f32_e32 v165, v165
	v_pk_mul_f32 v[162:163], v[118:119], v[162:163]
	v_pk_mul_f32 v[164:165], v[120:121], v[164:165]
	v_pk_mul_f32 v[162:163], v[126:127], v[162:163]
	v_pk_mul_f32 v[164:165], v[128:129], v[164:165]
	v_cvt_pk_bf16_f32 v174, v162, v163
	v_cvt_pk_bf16_f32 v175, v164, v165
	s_nop 1
	v_permlane16_swap_b32_e32 v172, v174
	v_permlane16_swap_b32_e32 v173, v175
	global_store_dwordx4 v176, v[172:175], s[4:5] offset:2048 sc1
	s_add_u32 s10, s10, 32
	s_cmp_lt_u32 s10, 64
	s_cbranch_scc1 .Lg2_a_item1
	s_cmp_lt_u32 s15, 16
	s_cbranch_scc0 .Lg2_a_noleft5
	s_lshr_b32 s12, s15, 3
	s_add_u32 s12, s12, 4
	s_mov_b32 s11, 10
	s_and_b32 s16, s15, 3
	s_lshl_b32 s16, s16, 6
	s_and_b32 s17, s14, 3
	s_mul_i32 s17, s17, 6
	s_add_u32 s12, s12, s17
	s_lshl_b32 s12, s12, 8
	s_add_u32 s12, s12, s16
	s_lshr_b32 s17, s14, 2
	s_mul_i32 s17, s17, 22
	s_lshl_b32 s11, s11, 1
	s_add_u32 s11, s11, s17
	s_bfe_u32 s17, s15, 0x10002
	s_add_u32 s11, s11, s17
	s_lshl_b32 s16, s12, 11
	s_add_u32 s0, s24, s16
	s_addc_u32 s1, s25, 0
	s_lshl_b32 s16, s11, 18
	s_add_u32 s2, s40, s16
	s_addc_u32 s3, s41, 0
	s_mul_i32 s16, s12, 0x1600
	s_lshl_b32 s17, s11, 11
	s_add_u32 s16, s16, s17
	s_add_u32 s4, s26, s16
	s_addc_u32 s5, s27, 0
	v_lshrrev_b32_e32 v141, 8, v142
	v_lshlrev_b32_e32 v141, 17, v141
	v_sub_u32_e32 v141, v136, v141
	s_and_b32 s17, s6, 0xfff
	s_add_u32 m0, s17, 0x0
	s_nop 0
	global_load_lds_dwordx4 v141, s[0:1]
	s_add_u32 m0, s6, 0x4000
	s_nop 0
	global_load_lds_dwordx4 v136, s[2:3]
	s_add_u32 s0, s0, 1024
	s_addc_u32 s1, s1, 0
	s_add_u32 s2, s2, 1024
	s_addc_u32 s3, s3, 0
	s_add_u32 m0, s17, 0x8000
	s_nop 0
	global_load_lds_dwordx4 v141, s[0:1]
	s_add_u32 m0, s6, 0xc000
	s_nop 0
	global_load_lds_dwordx4 v136, s[2:3]
	s_add_u32 s0, s0, 1024
	s_addc_u32 s1, s1, 0
	s_add_u32 s2, s2, 1024
	s_addc_u32 s3, s3, 0
	s_add_u32 m0, s17, 0x10000
	s_nop 0
	global_load_lds_dwordx4 v141, s[0:1]
	s_add_u32 m0, s6, 0x14000
	s_nop 0
	global_load_lds_dwordx4 v136, s[2:3]
	s_add_u32 s0, s0, 1024
	s_addc_u32 s1, s1, 0
	s_add_u32 s2, s2, 1024
	s_addc_u32 s3, s3, 0
	v_lshrrev_b32_e32 v140, 7, v142
	v_lshlrev_b32_e32 v139, 12, v140
	v_sub_u32_e32 v134, v134, v139
	v_lshl_add_u32 v134, v140, 10, v134
	v_mul_u32_u24_e32 v139, 0x42000, v140
	v_sub_u32_e32 v138, v138, v139
	v_mov_b32_e32 v2, 0
	v_mov_b32_e32 v3, 0
	v_mov_b32_e32 v4, 0
	v_mov_b32_e32 v5, 0
	v_mov_b32_e32 v6, 0
	v_mov_b32_e32 v7, 0
	v_mov_b32_e32 v8, 0
	v_mov_b32_e32 v9, 0
	v_mov_b32_e32 v10, 0
	v_mov_b32_e32 v11, 0
	v_mov_b32_e32 v12, 0
	v_mov_b32_e32 v13, 0
	v_mov_b32_e32 v14, 0
	v_mov_b32_e32 v15, 0
	v_mov_b32_e32 v16, 0
	v_mov_b32_e32 v17, 0

.Lg2_a_klB8:
	s_waitcnt vmcnt(4)
	s_barrier
	v_add_u32_e32 v139, 0x0, v134
	v_add_u32_e32 v140, 0x0, v135
	ds_read_b128 v[162:165], v139
	ds_read_b128 v[194:197], v140 offset:0
	ds_read_b128 v[198:201], v140 offset:1024
	ds_read_b128 v[202:205], v140 offset:2048
	ds_read_b128 v[206:209], v140 offset:3072
	s_add_u32 m0, s17, 0x18000
	s_nop 0
	global_load_lds_dwordx4 v141, s[0:1]
	s_add_u32 m0, s6, 0x1c000
	s_nop 0
	global_load_lds_dwordx4 v136, s[2:3]
	s_add_u32 s0, s0, 1024
	s_addc_u32 s1, s1, 0
	s_add_u32 s2, s2, 1024
	s_addc_u32 s3, s3, 0
	s_waitcnt lgkmcnt(0)
	v_mfma_f32_16x16x32_bf16 v[2:5], v[194:197], v[162:165], v[2:5]
	v_mfma_f32_16x16x32_bf16 v[6:9], v[198:201], v[162:165], v[6:9]
	v_mfma_f32_16x16x32_bf16 v[10:13], v[202:205], v[162:165], v[10:13]
	v_mfma_f32_16x16x32_bf16 v[14:17], v[206:209], v[162:165], v[14:17]
	s_waitcnt vmcnt(4)
	s_barrier
	v_add_u32_e32 v139, 0x8000, v134
	v_add_u32_e32 v140, 0x8000, v135
	ds_read_b128 v[162:165], v139
	ds_read_b128 v[194:197], v140 offset:0
	ds_read_b128 v[198:201], v140 offset:1024
	ds_read_b128 v[202:205], v140 offset:2048
	ds_read_b128 v[206:209], v140 offset:3072
	s_add_u32 m0, s17, 0x0
	s_nop 0
	global_load_lds_dwordx4 v141, s[0:1]
	s_add_u32 m0, s6, 0x4000
	s_nop 0
	global_load_lds_dwordx4 v136, s[2:3]
	s_add_u32 s0, s0, 1024
	s_addc_u32 s1, s1, 0
	s_add_u32 s2, s2, 1024
	s_addc_u32 s3, s3, 0
	s_waitcnt lgkmcnt(0)
	v_mfma_f32_16x16x32_bf16 v[2:5], v[194:197], v[162:165], v[2:5]
	v_mfma_f32_16x16x32_bf16 v[6:9], v[198:201], v[162:165], v[6:9]
	v_mfma_f32_16x16x32_bf16 v[10:13], v[202:205], v[162:165], v[10:13]
	v_mfma_f32_16x16x32_bf16 v[14:17], v[206:209], v[162:165], v[14:17]
	s_waitcnt vmcnt(4)
	s_barrier
	v_add_u32_e32 v139, 0x10000, v134
	v_add_u32_e32 v140, 0x10000, v135
	ds_read_b128 v[162:165], v139
	ds_read_b128 v[194:197], v140 offset:0
	ds_read_b128 v[198:201], v140 offset:1024
	ds_read_b128 v[202:205], v140 offset:2048
	ds_read_b128 v[206:209], v140 offset:3072
	s_add_u32 m0, s17, 0x8000
	s_nop 0
	global_load_lds_dwordx4 v141, s[0:1]
	s_add_u32 m0, s6, 0xc000
	s_nop 0
	global_load_lds_dwordx4 v136, s[2:3]
	s_add_u32 s0, s0, 1024
	s_addc_u32 s1, s1, 0
	s_add_u32 s2, s2, 1024
	s_addc_u32 s3, s3, 0
	s_waitcnt lgkmcnt(0)
	v_mfma_f32_16x16x32_bf16 v[2:5], v[194:197], v[162:165], v[2:5]
	v_mfma_f32_16x16x32_bf16 v[6:9], v[198:201], v[162:165], v[6:9]
	v_mfma_f32_16x16x32_bf16 v[10:13], v[202:205], v[162:165], v[10:13]
	v_mfma_f32_16x16x32_bf16 v[14:17], v[206:209], v[162:165], v[14:17]
	s_waitcnt vmcnt(4)
	s_barrier
	v_add_u32_e32 v139, 0x18000, v134
	v_add_u32_e32 v140, 0x18000, v135
	ds_read_b128 v[162:165], v139
	ds_read_b128 v[194:197], v140 offset:0
	ds_read_b128 v[198:201], v140 offset:1024
	ds_read_b128 v[202:205], v140 offset:2048
	ds_read_b128 v[206:209], v140 offset:3072
	s_add_u32 m0, s17, 0x10000
	s_nop 0
	global_load_lds_dwordx4 v141, s[0:1]
	s_add_u32 m0, s6, 0x14000
	s_nop 0
	global_load_lds_dwordx4 v136, s[2:3]
	s_add_u32 s0, s0, 1024
	s_addc_u32 s1, s1, 0
	s_add_u32 s2, s2, 1024
	s_addc_u32 s3, s3, 0
	s_waitcnt lgkmcnt(0)
	v_mfma_f32_16x16x32_bf16 v[2:5], v[194:197], v[162:165], v[2:5]
	v_mfma_f32_16x16x32_bf16 v[6:9], v[198:201], v[162:165], v[6:9]
	v_mfma_f32_16x16x32_bf16 v[10:13], v[202:205], v[162:165], v[10:13]
	v_mfma_f32_16x16x32_bf16 v[14:17], v[206:209], v[162:165], v[14:17]
	s_sub_u32 s7, s7, 1
	s_cmp_lg_u32 s7, 0
	s_cbranch_scc1 .Lg2_a_klB8
	s_waitcnt vmcnt(4)
	s_barrier
	v_add_u32_e32 v139, 0x0, v134
	v_add_u32_e32 v140, 0x0, v135
	ds_read_b128 v[162:165], v139
	ds_read_b128 v[194:197], v140 offset:0
	ds_read_b128 v[198:201], v140 offset:1024
	ds_read_b128 v[202:205], v140 offset:2048
	ds_read_b128 v[206:209], v140 offset:3072
	s_add_u32 m0, s17, 0x18000
	s_nop 0
	global_load_lds_dwordx4 v141, s[0:1]
	s_add_u32 m0, s6, 0x1c000
	s_nop 0
	global_load_lds_dwordx4 v136, s[2:3]
	s_add_u32 s0, s0, 1024
	s_addc_u32 s1, s1, 0
	s_add_u32 s2, s2, 1024
	s_addc_u32 s3, s3, 0
	s_waitcnt lgkmcnt(0)
	v_mfma_f32_16x16x32_bf16 v[2:5], v[194:197], v[162:165], v[2:5]
	v_mfma_f32_16x16x32_bf16 v[6:9], v[198:201], v[162:165], v[6:9]
	v_mfma_f32_16x16x32_bf16 v[10:13], v[202:205], v[162:165], v[10:13]
	v_mfma_f32_16x16x32_bf16 v[14:17], v[206:209], v[162:165], v[14:17]
	s_waitcnt vmcnt(4)
	s_barrier
	v_add_u32_e32 v139, 0x8000, v134
	v_add_u32_e32 v140, 0x8000, v135
	ds_read_b128 v[162:165], v139
	ds_read_b128 v[194:197], v140 offset:0
	ds_read_b128 v[198:201], v140 offset:1024
	ds_read_b128 v[202:205], v140 offset:2048
	ds_read_b128 v[206:209], v140 offset:3072
	s_waitcnt lgkmcnt(0)
	v_mfma_f32_16x16x32_bf16 v[2:5], v[194:197], v[162:165], v[2:5]
	v_mfma_f32_16x16x32_bf16 v[6:9], v[198:201], v[162:165], v[6:9]
	v_mfma_f32_16x16x32_bf16 v[10:13], v[202:205], v[162:165], v[10:13]
	v_mfma_f32_16x16x32_bf16 v[14:17], v[206:209], v[162:165], v[14:17]
	s_waitcnt vmcnt(2)
	s_barrier
	v_add_u32_e32 v139, 0x10000, v134
	v_add_u32_e32 v140, 0x10000, v135
	ds_read_b128 v[162:165], v139
	ds_read_b128 v[194:197], v140 offset:0
	ds_read_b128 v[198:201], v140 offset:1024
	ds_read_b128 v[202:205], v140 offset:2048
	ds_read_b128 v[206:209], v140 offset:3072
	s_waitcnt lgkmcnt(0)
	v_mfma_f32_16x16x32_bf16 v[2:5], v[194:197], v[162:165], v[2:5]
	v_mfma_f32_16x16x32_bf16 v[6:9], v[198:201], v[162:165], v[6:9]
	v_mfma_f32_16x16x32_bf16 v[10:13], v[202:205], v[162:165], v[10:13]
	v_mfma_f32_16x16x32_bf16 v[14:17], v[206:209], v[162:165], v[14:17]
	s_waitcnt vmcnt(0)
	s_barrier
	v_add_u32_e32 v139, 0x18000, v134
	v_add_u32_e32 v140, 0x18000, v135
	ds_read_b128 v[162:165], v139
	ds_read_b128 v[194:197], v140 offset:0
	ds_read_b128 v[198:201], v140 offset:1024
	ds_read_b128 v[202:205], v140 offset:2048
	ds_read_b128 v[206:209], v140 offset:3072
	s_waitcnt lgkmcnt(0)
	v_mfma_f32_16x16x32_bf16 v[2:5], v[194:197], v[162:165], v[2:5]
	v_mfma_f32_16x16x32_bf16 v[6:9], v[198:201], v[162:165], v[6:9]
	v_mfma_f32_16x16x32_bf16 v[10:13], v[202:205], v[162:165], v[10:13]
	v_mfma_f32_16x16x32_bf16 v[14:17], v[206:209], v[162:165], v[14:17]
.Lg2_a_kdone7:
	s_nop 7
	s_nop 1
	v_mov_b32_e32 v166, 0xbfb8aa3b
	v_mov_b32_e32 v167, 0xbfb8aa3b
	v_mov_b32_e32 v178, 1.0
	v_mov_b32_e32 v179, 1.0
	v_mov_b32_e32 v176, v138
	v_pk_mul_f32 v[162:163], v[2:3], v[166:167]
	v_pk_mul_f32 v[164:165], v[4:5], v[166:167]
	v_exp_f32_e32 v162, v162
	v_exp_f32_e32 v163, v163
	v_exp_f32_e32 v164, v164
	v_exp_f32_e32 v165, v165
	v_pk_add_f32 v[162:163], v[162:163], v[178:179]
	v_pk_add_f32 v[164:165], v[164:165], v[178:179]
	v_rcp_f32_e32 v162, v162
	v_rcp_f32_e32 v163, v163
	v_rcp_f32_e32 v164, v164
	v_rcp_f32_e32 v165, v165
	v_pk_mul_f32 v[162:163], v[2:3], v[162:163]
	v_pk_mul_f32 v[164:165], v[4:5], v[164:165]
	v_pk_mul_f32 v[162:163], v[10:11], v[162:163]
	v_pk_mul_f32 v[164:165], v[12:13], v[164:165]
	v_cvt_pk_bf16_f32 v168, v162, v163
	v_cvt_pk_bf16_f32 v169, v164, v165
	v_pk_mul_f32 v[162:163], v[6:7], v[166:167]
	v_pk_mul_f32 v[164:165], v[8:9], v[166:167]
	v_exp_f32_e32 v162, v162
	v_exp_f32_e32 v163, v163
	v_exp_f32_e32 v164, v164
	v_exp_f32_e32 v165, v165
	v_pk_add_f32 v[162:163], v[162:163], v[178:179]
	v_pk_add_f32 v[164:165], v[164:165], v[178:179]
	v_rcp_f32_e32 v162, v162
	v_rcp_f32_e32 v163, v163
	v_rcp_f32_e32 v164, v164
	v_rcp_f32_e32 v165, v165
	v_pk_mul_f32 v[162:163], v[6:7], v[162:163]
	v_pk_mul_f32 v[164:165], v[8:9], v[164:165]
	v_pk_mul_f32 v[162:163], v[14:15], v[162:163]
	v_pk_mul_f32 v[164:165], v[16:17], v[164:165]
	v_cvt_pk_bf16_f32 v170, v162, v163
	v_cvt_pk_bf16_f32 v171, v164, v165
	s_nop 1
	v_permlane16_swap_b32_e32 v168, v170
	v_permlane16_swap_b32_e32 v169, v171
	global_store_dwordx4 v176, v[168:171], s[4:5] offset:0 sc1
